# v11 with the waves 4-7 static priority raise kept through the gMLP part (reset moved to the phase-closing barrier)
# baseline (speedup 1.0000x reference)
; DI void grid_bar(unsigned* ctr, unsigned target, int tid) {
;     asm volatile("s_waitcnt vmcnt(0)" ::: "memory");
;     __syncthreads();
;     if (tid == 0) {
;         __builtin_amdgcn_fence(__ATOMIC_RELEASE, "agent");
;         asm volatile("s_waitcnt vmcnt(0)" ::: "memory");
;         __hip_atomic_fetch_add(ctr, 1u, __ATOMIC_RELAXED, __HIP_MEMORY_SCOPE_AGENT);
;         while (__hip_atomic_load(ctr, __ATOMIC_RELAXED, __HIP_MEMORY_SCOPE_AGENT) < target) __builtin_amdgcn_s_sleep(1);
.LBB0_572:
	s_mov_b64 s[2:3], s[76:77]
	s_mov_b32 s0, s75
	v_mov_b32_e32 v0, 0
	s_waitcnt vmcnt(0)
	s_lshl_b32 s0, s0, 6
	v_mbcnt_lo_u32_b32 v0, -1, v0
	v_mbcnt_hi_u32_b32 v0, -1, v0
	v_sub_u32_e32 v0, 0, v0
	v_cmp_eq_u32_e32 vcc, s0, v0
	s_waitcnt lgkmcnt(0)
	s_setprio 0
	s_barrier
	s_and_saveexec_b64 s[0:1], vcc
	s_cbranch_execz .LBB0_578
	s_load_dwordx2 s[2:3], s[2:3], 0xf0
	v_readlane_b32 s6, v253, 12
	s_lshl_b32 s6, s6, 2
	s_mov_b64 s[4:5], exec
	buffer_wbl2 sc1
	s_waitcnt vmcnt(0) lgkmcnt(0)
	s_add_u32 s2, s2, s6
	s_waitcnt vmcnt(0)
	s_addc_u32 s3, s3, 0
	v_mbcnt_lo_u32_b32 v0, s4, 0
	s_add_u32 s2, s2, 0x3f400000
	v_mbcnt_hi_u32_b32 v0, s5, v0
	s_addc_u32 s3, s3, 0
	v_cmp_eq_u32_e32 vcc, 0, v0
	s_and_saveexec_b64 s[6:7], vcc
	s_cbranch_execz .LBB0_575
	s_bcnt1_i32_b64 s4, s[4:5]
	v_mov_b32_e32 v0, 0
	v_mov_b32_e32 v1, s4
	global_atomic_add v0, v1, s[2:3]
